# GLU epilogues: Y5/bias loads hoisted to the top of each iteration (no per-row-group vmcnt waits); phase 4b half-tile epilogue software-pipelined like the full-tile one
# speedup vs baseline: 1.0195x; 1.0096x over previous
.LBB0_663:
	global_load_dwordx4 v[232:235], v[10:11], off
	v_lshl_add_u64 v[4:5], v[8:9], 0, v[66:67]
	global_load_dwordx4 v[240:243], v[4:5], off
	v_add_u32_e32 v6, s14, v94
	v_add_u32_e32 v7, s14, v92
	ds_read_b128 v[22:25], v6
	ds_read_b128 v[26:29], v7
	v_add_u32_e32 v16, s14, v89
	v_add_u32_e32 v17, s14, v86
	v_mov_b32_e32 v33, v67
	v_mov_b32_e32 v37, v67
	ds_read_b128 v[38:41], v16
	ds_read_b128 v[4:7], v17
	v_lshl_add_u64 v[48:49], v[8:9], 0, v[32:33]
	v_lshl_add_u64 v[16:17], v[12:13], 0, v[32:33]
	v_lshl_add_u64 v[30:31], v[8:9], 0, v[36:37]
	v_lshl_add_u64 v[42:43], v[12:13], 0, v[36:37]
	v_mov_b32_e32 v35, v67
	v_lshl_add_u64 v[44:45], v[8:9], 0, v[34:35]
	global_load_dwordx4 v[244:247], v[30:31], off
	global_load_dwordx4 v[248:251], v[44:45], off
	global_load_dwordx4 v[252:255], v[48:49], off
	v_lshl_add_u64 v[46:47], v[12:13], 0, v[34:35]
	v_lshl_add_u64 v[14:15], v[12:13], 0, v[66:67]
	s_addk_i32 s14, 0x4200
	v_add_u32_e32 v66, 0x10000, v66
	v_add_u32_e32 v32, 0x10000, v32
	v_add_u32_e32 v34, 0x10000, v34
	v_add_u32_e32 v36, 0x10000, v36
	s_cmpk_lg_u32 s14, 0x8400
	s_waitcnt vmcnt(0) lgkmcnt(3)
	v_mov_b32_e32 v0, v232
	v_mov_b32_e32 v1, v233
	v_mov_b32_e32 v2, v234
	v_mov_b32_e32 v3, v235
	v_add_f32_e32 v0, v22, v0
	v_add_f32_e32 v2, v24, v2
	v_add_f32_e32 v3, v25, v3
	v_mul_f32_e32 v22, 0xbfb8aa3b, v0
	v_mul_f32_e32 v24, 0xbfb8aa3b, v2
	v_add_f32_e32 v1, v23, v1
	v_mul_f32_e32 v25, 0xbfb8aa3b, v3
	v_exp_f32_e32 v2, v22
	v_exp_f32_e32 v3, v24
	v_mul_f32_e32 v23, 0xbfb8aa3b, v1
	v_mov_b32_e32 v18, v240
	v_mov_b32_e32 v19, v241
	v_mov_b32_e32 v20, v242
	v_mov_b32_e32 v21, v243
	v_mov_b32_e32 v0, v18
	v_mov_b32_e32 v1, v20
	v_mov_b32_e32 v20, v19
	v_exp_f32_e32 v18, v23
	v_exp_f32_e32 v19, v25
	v_pk_add_f32 v[2:3], v[2:3], 1.0 op_sel_hi:[1,0]
	v_pk_add_f32 v[18:19], v[18:19], 1.0 op_sel_hi:[1,0]
	v_div_scale_f32 v22, s[10:11], v3, v3, 1.0
	v_div_scale_f32 v24, s[10:11], v2, v2, 1.0
	v_rcp_f32_e32 v51, v22
	v_div_scale_f32 v33, s[12:13], v19, v19, 1.0
	v_rcp_f32_e32 v52, v24
	v_div_scale_f32 v37, s[16:17], v18, v18, 1.0
	v_rcp_f32_e32 v53, v33
	v_rcp_f32_e32 v54, v37
	v_fma_f32 v55, -v22, v51, 1.0
	v_div_scale_f32 v23, vcc, 1.0, v3, 1.0
	v_fma_f32 v56, -v24, v52, 1.0
	v_fmac_f32_e32 v51, v55, v51
	v_div_scale_f32 v25, s[10:11], 1.0, v2, 1.0
	v_fma_f32 v57, -v33, v53, 1.0
	v_fmac_f32_e32 v52, v56, v52
	v_mul_f32_e32 v55, v23, v51
	v_div_scale_f32 v35, s[12:13], 1.0, v19, 1.0
	v_fma_f32 v58, -v37, v54, 1.0
	v_fmac_f32_e32 v53, v57, v53
	v_mul_f32_e32 v56, v25, v52
	v_fma_f32 v59, -v22, v55, v23
	v_div_scale_f32 v50, s[16:17], 1.0, v18, 1.0
	v_fmac_f32_e32 v54, v58, v54
	v_mul_f32_e32 v57, v35, v53
	v_fma_f32 v60, -v24, v56, v25
	v_fmac_f32_e32 v55, v59, v51
	v_mul_f32_e32 v58, v50, v54
	v_fma_f32 v61, -v33, v57, v35
	v_fmac_f32_e32 v56, v60, v52
	v_fma_f32 v22, -v22, v55, v23
	v_fma_f32 v62, -v37, v58, v50
	v_fmac_f32_e32 v57, v61, v53
	v_fma_f32 v23, -v24, v56, v25
	v_div_fmas_f32 v22, v22, v51, v55
	s_mov_b64 vcc, s[10:11]
	v_fmac_f32_e32 v58, v62, v54
	v_fma_f32 v24, -v33, v57, v35
	v_div_fixup_f32 v3, v22, v3, 1.0
	v_div_fmas_f32 v22, v23, v52, v56
	s_mov_b64 vcc, s[12:13]
	v_fma_f32 v25, -v37, v58, v50
	v_div_fixup_f32 v2, v22, v2, 1.0
	v_div_fmas_f32 v22, v24, v53, v57
	s_mov_b64 vcc, s[16:17]
	v_pk_mul_f32 v[0:1], v[0:1], v[2:3]
	v_div_fmas_f32 v2, v25, v54, v58
	v_div_fixup_f32 v3, v22, v19, 1.0
	v_div_fixup_f32 v2, v2, v18, 1.0
	v_and_b32_sdwa v18, v1, v110 dst_sel:DWORD dst_unused:UNUSED_PAD src0_sel:WORD_1 src1_sel:DWORD
	v_and_b32_sdwa v19, v0, v110 dst_sel:DWORD dst_unused:UNUSED_PAD src0_sel:WORD_1 src1_sel:DWORD
	v_pk_mul_f32 v[2:3], v[20:21], v[2:3]
	v_add3_u32 v0, v0, v19, s3
	v_add3_u32 v1, v1, v18, s3
	v_and_b32_sdwa v18, v3, v110 dst_sel:DWORD dst_unused:UNUSED_PAD src0_sel:WORD_1 src1_sel:DWORD
	v_and_b32_sdwa v19, v2, v110 dst_sel:DWORD dst_unused:UNUSED_PAD src0_sel:WORD_1 src1_sel:DWORD
	v_add3_u32 v3, v3, v18, s3
	v_add3_u32 v2, v2, v19, s3
	v_and_b32_e32 v3, 0xffff0000, v3
	v_and_b32_e32 v2, 0xffff0000, v2
	v_or_b32_sdwa v1, v3, v1 dst_sel:DWORD dst_unused:UNUSED_PAD src0_sel:DWORD src1_sel:WORD_1
	v_or_b32_sdwa v0, v2, v0 dst_sel:DWORD dst_unused:UNUSED_PAD src0_sel:DWORD src1_sel:WORD_1
	global_store_dwordx2 v[14:15], v[0:1], off
	s_nop 1
	v_mov_b32_e32 v0, v232
	v_mov_b32_e32 v1, v233
	v_mov_b32_e32 v2, v234
	v_mov_b32_e32 v3, v235
	s_nop 0
	s_waitcnt lgkmcnt(2)
	v_add_f32_e32 v14, v26, v0
	v_add_f32_e32 v2, v28, v2
	v_add_f32_e32 v3, v29, v3
	v_mov_b32_e32 v18, v244
	v_mov_b32_e32 v19, v245
	v_mov_b32_e32 v20, v246
	v_mov_b32_e32 v21, v247
	v_mov_b32_e32 v0, v18
	v_mul_f32_e32 v14, 0xbfb8aa3b, v14
	v_mul_f32_e32 v18, 0xbfb8aa3b, v2
	v_add_f32_e32 v15, v27, v1
	v_mov_b32_e32 v1, v20
	v_mov_b32_e32 v20, v19
	v_mul_f32_e32 v19, 0xbfb8aa3b, v3
	v_exp_f32_e32 v2, v14
	v_exp_f32_e32 v3, v18
	v_mul_f32_e32 v15, 0xbfb8aa3b, v15
	v_exp_f32_e32 v14, v15
	v_exp_f32_e32 v15, v19
	v_pk_add_f32 v[2:3], v[2:3], 1.0 op_sel_hi:[1,0]
	v_pk_add_f32 v[14:15], v[14:15], 1.0 op_sel_hi:[1,0]
	v_div_scale_f32 v18, s[10:11], v3, v3, 1.0
	v_div_scale_f32 v22, s[10:11], v2, v2, 1.0
	v_rcp_f32_e32 v28, v18
	v_div_scale_f32 v24, s[12:13], v15, v15, 1.0
	v_rcp_f32_e32 v29, v22
	v_div_scale_f32 v26, s[16:17], v14, v14, 1.0
	v_rcp_f32_e32 v30, v24
	v_rcp_f32_e32 v31, v26
	v_fma_f32 v33, -v18, v28, 1.0
	v_div_scale_f32 v19, vcc, 1.0, v3, 1.0
	v_fma_f32 v35, -v22, v29, 1.0
	v_fmac_f32_e32 v28, v33, v28
	v_div_scale_f32 v23, s[10:11], 1.0, v2, 1.0
	v_fma_f32 v37, -v24, v30, 1.0
	v_fmac_f32_e32 v29, v35, v29
	v_mul_f32_e32 v33, v19, v28
	v_div_scale_f32 v25, s[12:13], 1.0, v15, 1.0
	v_fma_f32 v50, -v26, v31, 1.0
	v_fmac_f32_e32 v30, v37, v30
	v_mul_f32_e32 v35, v23, v29
	v_fma_f32 v51, -v18, v33, v19
	v_div_scale_f32 v27, s[16:17], 1.0, v14, 1.0
	v_fmac_f32_e32 v31, v50, v31
	v_mul_f32_e32 v37, v25, v30
	v_fma_f32 v52, -v22, v35, v23
	v_fmac_f32_e32 v33, v51, v28
	v_mul_f32_e32 v50, v27, v31
	v_fma_f32 v53, -v24, v37, v25
	v_fmac_f32_e32 v35, v52, v29
	v_fma_f32 v18, -v18, v33, v19
	v_fma_f32 v54, -v26, v50, v27
	v_fmac_f32_e32 v37, v53, v30
	v_fma_f32 v19, -v22, v35, v23
	v_div_fmas_f32 v18, v18, v28, v33
	s_mov_b64 vcc, s[10:11]
	v_fmac_f32_e32 v50, v54, v31
	v_fma_f32 v22, -v24, v37, v25
	v_div_fixup_f32 v3, v18, v3, 1.0
	v_div_fmas_f32 v18, v19, v29, v35
	s_mov_b64 vcc, s[12:13]
	v_fma_f32 v23, -v26, v50, v27
	v_div_fixup_f32 v2, v18, v2, 1.0
	v_div_fmas_f32 v18, v22, v30, v37
	s_mov_b64 vcc, s[16:17]
	v_pk_mul_f32 v[0:1], v[0:1], v[2:3]
	v_div_fmas_f32 v2, v23, v31, v50
	v_div_fixup_f32 v3, v18, v15, 1.0
	v_div_fixup_f32 v2, v2, v14, 1.0
	v_and_b32_sdwa v14, v1, v110 dst_sel:DWORD dst_unused:UNUSED_PAD src0_sel:WORD_1 src1_sel:DWORD
	v_and_b32_sdwa v15, v0, v110 dst_sel:DWORD dst_unused:UNUSED_PAD src0_sel:WORD_1 src1_sel:DWORD
	v_pk_mul_f32 v[2:3], v[20:21], v[2:3]
	v_add3_u32 v0, v0, v15, s3
	v_add3_u32 v1, v1, v14, s3
	v_and_b32_sdwa v14, v3, v110 dst_sel:DWORD dst_unused:UNUSED_PAD src0_sel:WORD_1 src1_sel:DWORD
	v_and_b32_sdwa v15, v2, v110 dst_sel:DWORD dst_unused:UNUSED_PAD src0_sel:WORD_1 src1_sel:DWORD
	v_add3_u32 v3, v3, v14, s3
	v_add3_u32 v2, v2, v15, s3
	v_and_b32_e32 v3, 0xffff0000, v3
	v_and_b32_e32 v2, 0xffff0000, v2
	v_or_b32_sdwa v1, v3, v1 dst_sel:DWORD dst_unused:UNUSED_PAD src0_sel:DWORD src1_sel:WORD_1
	v_or_b32_sdwa v0, v2, v0 dst_sel:DWORD dst_unused:UNUSED_PAD src0_sel:DWORD src1_sel:WORD_1
	global_store_dwordx2 v[42:43], v[0:1], off
	s_nop 1
	v_mov_b32_e32 v0, v232
	v_mov_b32_e32 v1, v233
	v_mov_b32_e32 v2, v234
	v_mov_b32_e32 v3, v235
	s_nop 0
	s_waitcnt lgkmcnt(1)
	v_add_f32_e32 v14, v38, v0
	v_add_f32_e32 v2, v40, v2
	v_add_f32_e32 v3, v41, v3
	v_mov_b32_e32 v18, v248
	v_mov_b32_e32 v19, v249
	v_mov_b32_e32 v20, v250
	v_mov_b32_e32 v21, v251
	v_mov_b32_e32 v0, v18
	v_mul_f32_e32 v14, 0xbfb8aa3b, v14
	v_mul_f32_e32 v18, 0xbfb8aa3b, v2
	v_add_f32_e32 v15, v39, v1
	v_mov_b32_e32 v1, v20
	v_mov_b32_e32 v20, v19
	v_mul_f32_e32 v19, 0xbfb8aa3b, v3
	v_exp_f32_e32 v2, v14
	v_exp_f32_e32 v3, v18
	v_mul_f32_e32 v15, 0xbfb8aa3b, v15
	v_exp_f32_e32 v14, v15
	v_exp_f32_e32 v15, v19
	v_pk_add_f32 v[2:3], v[2:3], 1.0 op_sel_hi:[1,0]
	v_pk_add_f32 v[14:15], v[14:15], 1.0 op_sel_hi:[1,0]
	v_div_scale_f32 v18, s[10:11], v3, v3, 1.0
	v_div_scale_f32 v22, s[10:11], v2, v2, 1.0
	v_rcp_f32_e32 v28, v18
	v_div_scale_f32 v24, s[12:13], v15, v15, 1.0
	v_rcp_f32_e32 v29, v22
	v_div_scale_f32 v26, s[16:17], v14, v14, 1.0
	v_rcp_f32_e32 v30, v24
	v_rcp_f32_e32 v31, v26
	v_fma_f32 v33, -v18, v28, 1.0
	v_div_scale_f32 v19, vcc, 1.0, v3, 1.0
	v_fma_f32 v35, -v22, v29, 1.0
	v_fmac_f32_e32 v28, v33, v28
	v_div_scale_f32 v23, s[10:11], 1.0, v2, 1.0
	v_fma_f32 v37, -v24, v30, 1.0
	v_fmac_f32_e32 v29, v35, v29
	v_mul_f32_e32 v33, v19, v28
	v_div_scale_f32 v25, s[12:13], 1.0, v15, 1.0
	v_fma_f32 v38, -v26, v31, 1.0
	v_fmac_f32_e32 v30, v37, v30
	v_mul_f32_e32 v35, v23, v29
	v_fma_f32 v39, -v18, v33, v19
	v_div_scale_f32 v27, s[16:17], 1.0, v14, 1.0
	v_fmac_f32_e32 v31, v38, v31
	v_mul_f32_e32 v37, v25, v30
	v_fma_f32 v40, -v22, v35, v23
	v_fmac_f32_e32 v33, v39, v28
	v_mul_f32_e32 v38, v27, v31
	v_fma_f32 v41, -v24, v37, v25
	v_fmac_f32_e32 v35, v40, v29
	v_fma_f32 v18, -v18, v33, v19
	v_fma_f32 v42, -v26, v38, v27
	v_fmac_f32_e32 v37, v41, v30
	v_fma_f32 v19, -v22, v35, v23
	v_div_fmas_f32 v18, v18, v28, v33
	s_mov_b64 vcc, s[10:11]
	v_fmac_f32_e32 v38, v42, v31
	v_fma_f32 v22, -v24, v37, v25
	v_div_fixup_f32 v3, v18, v3, 1.0
	v_div_fmas_f32 v18, v19, v29, v35
	s_mov_b64 vcc, s[12:13]
	v_fma_f32 v23, -v26, v38, v27
	v_div_fixup_f32 v2, v18, v2, 1.0
	v_div_fmas_f32 v18, v22, v30, v37
	s_mov_b64 vcc, s[16:17]
	v_pk_mul_f32 v[0:1], v[0:1], v[2:3]
	v_div_fmas_f32 v2, v23, v31, v38
	v_div_fixup_f32 v3, v18, v15, 1.0
	v_div_fixup_f32 v2, v2, v14, 1.0
	v_and_b32_sdwa v14, v1, v110 dst_sel:DWORD dst_unused:UNUSED_PAD src0_sel:WORD_1 src1_sel:DWORD
	v_and_b32_sdwa v15, v0, v110 dst_sel:DWORD dst_unused:UNUSED_PAD src0_sel:WORD_1 src1_sel:DWORD
	v_pk_mul_f32 v[2:3], v[20:21], v[2:3]
	v_add3_u32 v0, v0, v15, s3
	v_add3_u32 v1, v1, v14, s3
	v_and_b32_sdwa v14, v3, v110 dst_sel:DWORD dst_unused:UNUSED_PAD src0_sel:WORD_1 src1_sel:DWORD
	v_and_b32_sdwa v15, v2, v110 dst_sel:DWORD dst_unused:UNUSED_PAD src0_sel:WORD_1 src1_sel:DWORD
	v_add3_u32 v3, v3, v14, s3
	v_add3_u32 v2, v2, v15, s3
	v_and_b32_e32 v3, 0xffff0000, v3
	v_and_b32_e32 v2, 0xffff0000, v2
	v_or_b32_sdwa v1, v3, v1 dst_sel:DWORD dst_unused:UNUSED_PAD src0_sel:DWORD src1_sel:WORD_1
	v_or_b32_sdwa v0, v2, v0 dst_sel:DWORD dst_unused:UNUSED_PAD src0_sel:DWORD src1_sel:WORD_1
	global_store_dwordx2 v[46:47], v[0:1], off
	s_nop 1
	v_mov_b32_e32 v0, v232
	v_mov_b32_e32 v1, v233
	v_mov_b32_e32 v2, v234
	v_mov_b32_e32 v3, v235
	s_nop 0
	s_waitcnt lgkmcnt(0)
	v_add_f32_e32 v4, v4, v0
	v_add_f32_e32 v2, v6, v2
	v_add_f32_e32 v3, v7, v3
	v_mul_f32_e32 v4, 0xbfb8aa3b, v4
	v_mul_f32_e32 v6, 0xbfb8aa3b, v2
	v_add_f32_e32 v5, v5, v1
	v_mul_f32_e32 v7, 0xbfb8aa3b, v3
	v_exp_f32_e32 v2, v4
	v_exp_f32_e32 v3, v6
	v_mul_f32_e32 v5, 0xbfb8aa3b, v5
	v_exp_f32_e32 v4, v5
	v_exp_f32_e32 v5, v7
	v_pk_add_f32 v[2:3], v[2:3], 1.0 op_sel_hi:[1,0]
	v_mov_b32_e32 v18, v252
	v_mov_b32_e32 v19, v253
	v_mov_b32_e32 v20, v254
	v_mov_b32_e32 v21, v255
	v_mov_b32_e32 v0, v18
	v_div_scale_f32 v6, s[10:11], v3, v3, 1.0
	v_pk_add_f32 v[4:5], v[4:5], 1.0 op_sel_hi:[1,0]
	v_div_scale_f32 v14, s[10:11], v2, v2, 1.0
	v_rcp_f32_e32 v24, v6
	v_div_scale_f32 v18, s[12:13], v5, v5, 1.0
	v_rcp_f32_e32 v25, v14
	v_div_scale_f32 v22, s[16:17], v4, v4, 1.0
	v_rcp_f32_e32 v26, v18
	v_rcp_f32_e32 v27, v22
	v_fma_f32 v28, -v6, v24, 1.0
	v_div_scale_f32 v7, vcc, 1.0, v3, 1.0
	v_fma_f32 v29, -v14, v25, 1.0
	v_fmac_f32_e32 v24, v28, v24
	v_div_scale_f32 v15, s[10:11], 1.0, v2, 1.0
	v_fma_f32 v30, -v18, v26, 1.0
	v_fmac_f32_e32 v25, v29, v25
	v_mul_f32_e32 v28, v7, v24
	v_mov_b32_e32 v1, v20
	v_mov_b32_e32 v20, v19
	v_div_scale_f32 v19, s[12:13], 1.0, v5, 1.0
	v_fma_f32 v31, -v22, v27, 1.0
	v_fmac_f32_e32 v26, v30, v26
	v_mul_f32_e32 v29, v15, v25
	v_fma_f32 v33, -v6, v28, v7
	v_div_scale_f32 v23, s[16:17], 1.0, v4, 1.0
	v_fmac_f32_e32 v27, v31, v27
	v_mul_f32_e32 v30, v19, v26
	v_fma_f32 v35, -v14, v29, v15
	v_fmac_f32_e32 v28, v33, v24
	v_mul_f32_e32 v31, v23, v27
	v_fma_f32 v37, -v18, v30, v19
	v_fmac_f32_e32 v29, v35, v25
	v_fma_f32 v6, -v6, v28, v7
	v_fma_f32 v38, -v22, v31, v23
	v_fmac_f32_e32 v30, v37, v26
	v_fma_f32 v7, -v14, v29, v15
	v_div_fmas_f32 v6, v6, v24, v28
	s_mov_b64 vcc, s[10:11]
	v_fmac_f32_e32 v31, v38, v27
	v_fma_f32 v14, -v18, v30, v19
	v_div_fixup_f32 v3, v6, v3, 1.0
	v_div_fmas_f32 v6, v7, v25, v29
	s_mov_b64 vcc, s[12:13]
	v_fma_f32 v15, -v22, v31, v23
	v_div_fixup_f32 v2, v6, v2, 1.0
	v_div_fmas_f32 v6, v14, v26, v30
	s_mov_b64 vcc, s[16:17]
	v_pk_mul_f32 v[0:1], v[0:1], v[2:3]
	v_div_fmas_f32 v2, v15, v27, v31
	v_div_fixup_f32 v3, v6, v5, 1.0
	v_div_fixup_f32 v2, v2, v4, 1.0
	v_and_b32_sdwa v4, v1, v110 dst_sel:DWORD dst_unused:UNUSED_PAD src0_sel:WORD_1 src1_sel:DWORD
	v_and_b32_sdwa v5, v0, v110 dst_sel:DWORD dst_unused:UNUSED_PAD src0_sel:WORD_1 src1_sel:DWORD
	v_pk_mul_f32 v[2:3], v[20:21], v[2:3]
	v_add3_u32 v0, v0, v5, s3
	v_add3_u32 v1, v1, v4, s3
	v_and_b32_sdwa v4, v3, v110 dst_sel:DWORD dst_unused:UNUSED_PAD src0_sel:WORD_1 src1_sel:DWORD
	v_and_b32_sdwa v5, v2, v110 dst_sel:DWORD dst_unused:UNUSED_PAD src0_sel:WORD_1 src1_sel:DWORD
	v_add3_u32 v3, v3, v4, s3
	v_add3_u32 v2, v2, v5, s3
	v_and_b32_e32 v3, 0xffff0000, v3
	v_and_b32_e32 v2, 0xffff0000, v2
	v_or_b32_sdwa v1, v3, v1 dst_sel:DWORD dst_unused:UNUSED_PAD src0_sel:DWORD src1_sel:WORD_1
	v_or_b32_sdwa v0, v2, v0 dst_sel:DWORD dst_unused:UNUSED_PAD src0_sel:DWORD src1_sel:WORD_1
	global_store_dwordx2 v[16:17], v[0:1], off
	s_cbranch_scc1 .LBB0_663
	s_mov_b64 s[10:11], 0
	s_barrier

.LBB0_667:
	global_load_dwordx4 v[232:235], v[10:11], off
	v_ashrrev_i32_e32 v21, 31, v20
	v_ashrrev_i32_e32 v19, 31, v18
	v_ashrrev_i32_e32 v17, 31, v16
	v_lshlrev_b64 v[22:23], 11, v[20:21]
	v_lshlrev_b64 v[36:37], 11, v[18:19]
	v_lshlrev_b64 v[38:39], 11, v[16:17]
	v_lshl_add_u64 v[42:43], v[8:9], 0, v[22:23]
	v_lshl_add_u64 v[46:47], v[8:9], 0, v[36:37]
	v_lshl_add_u64 v[48:49], v[12:13], 0, v[36:37]
	v_lshl_add_u64 v[50:51], v[8:9], 0, v[38:39]
	v_lshl_add_u64 v[52:53], v[12:13], 0, v[38:39]
	global_load_dwordx4 v[240:243], v[42:43], off
	v_add_u32_e32 v4, s14, v94
	ds_read_b128 v[24:27], v4
	v_add_u32_e32 v5, s14, v92
	v_ashrrev_i32_e32 v15, 31, v14
	ds_read_b128 v[28:31], v5
	v_lshlrev_b64 v[40:41], 11, v[14:15]
	v_lshl_add_u64 v[44:45], v[12:13], 0, v[22:23]
	v_lshl_add_u64 v[54:55], v[8:9], 0, v[40:41]
	global_load_dwordx4 v[244:247], v[46:47], off
	global_load_dwordx4 v[248:251], v[50:51], off
	global_load_dwordx4 v[252:255], v[54:55], off
	v_lshl_add_u64 v[22:23], v[12:13], 0, v[40:41]
	v_add_u32_e32 v6, s14, v89
	v_add_u32_e32 v7, s14, v86
	ds_read_b128 v[32:35], v6
	ds_read_b128 v[4:7], v7
	s_addk_i32 s14, 0x4200
	v_add_u32_e32 v14, 32, v14
	v_add_u32_e32 v16, 32, v16
	v_add_u32_e32 v18, 32, v18
	v_add_u32_e32 v20, 32, v20
	s_cmp_lg_u32 s14, 0x10800
	s_waitcnt vmcnt(0) lgkmcnt(3)
	v_mov_b32_e32 v0, v232
	v_mov_b32_e32 v1, v233
	v_mov_b32_e32 v2, v234
	v_mov_b32_e32 v3, v235
	v_add_f32_e32 v0, v24, v0
	v_add_f32_e32 v1, v25, v1
	v_add_f32_e32 v2, v26, v2
	v_mul_f32_e32 v0, 0xbfb8aa3b, v0
	v_mul_f32_e32 v1, 0xbfb8aa3b, v1
	v_mul_f32_e32 v15, 0xbfb8aa3b, v2
	v_add_f32_e32 v3, v27, v3
	v_exp_f32_e32 v0, v0
	v_exp_f32_e32 v2, v1
	v_exp_f32_e32 v1, v15
	v_mul_f32_e32 v3, 0xbfb8aa3b, v3
	v_exp_f32_e32 v3, v3
	v_mov_b32_e32 v36, v240
	v_mov_b32_e32 v37, v241
	v_mov_b32_e32 v38, v242
	v_mov_b32_e32 v39, v243
	v_mov_b32_e32 v24, v36
	v_pk_add_f32 v[0:1], v[0:1], 1.0 op_sel_hi:[1,0]
	v_mov_b32_e32 v25, v38
	v_div_scale_f32 v15, s[10:11], v1, v1, 1.0
	v_pk_add_f32 v[2:3], v[2:3], 1.0 op_sel_hi:[1,0]
	v_div_scale_f32 v19, s[10:11], v0, v0, 1.0
	v_rcp_f32_e32 v40, v15
	v_div_scale_f32 v26, s[12:13], v3, v3, 1.0
	v_rcp_f32_e32 v41, v19
	v_div_scale_f32 v36, s[16:17], v2, v2, 1.0
	v_rcp_f32_e32 v42, v26
	v_rcp_f32_e32 v43, v36
	v_fma_f32 v56, -v15, v40, 1.0
	v_div_scale_f32 v17, vcc, 1.0, v1, 1.0
	v_fma_f32 v57, -v19, v41, 1.0
	v_fmac_f32_e32 v40, v56, v40
	v_div_scale_f32 v21, s[10:11], 1.0, v0, 1.0
	v_fma_f32 v58, -v26, v42, 1.0
	v_fmac_f32_e32 v41, v57, v41
	v_mul_f32_e32 v56, v17, v40
	v_div_scale_f32 v27, s[12:13], 1.0, v3, 1.0
	v_fma_f32 v59, -v36, v43, 1.0
	v_fmac_f32_e32 v42, v58, v42
	v_mul_f32_e32 v57, v21, v41
	v_fma_f32 v60, -v15, v56, v17
	v_mov_b32_e32 v38, v37
	v_div_scale_f32 v37, s[16:17], 1.0, v2, 1.0
	v_fmac_f32_e32 v43, v59, v43
	v_mul_f32_e32 v58, v27, v42
	v_fma_f32 v61, -v19, v57, v21
	v_fmac_f32_e32 v56, v60, v40
	v_mul_f32_e32 v59, v37, v43
	v_fma_f32 v62, -v26, v58, v27
	v_fmac_f32_e32 v57, v61, v41
	v_fma_f32 v15, -v15, v56, v17
	v_fma_f32 v63, -v36, v59, v37
	v_fmac_f32_e32 v58, v62, v42
	v_fma_f32 v17, -v19, v57, v21
	v_div_fmas_f32 v15, v15, v40, v56
	s_mov_b64 vcc, s[10:11]
	v_fmac_f32_e32 v59, v63, v43
	v_fma_f32 v19, -v26, v58, v27
	v_div_fixup_f32 v1, v15, v1, 1.0
	v_div_fmas_f32 v15, v17, v41, v57
	s_mov_b64 vcc, s[12:13]
	v_fma_f32 v21, -v36, v59, v37
	v_div_fixup_f32 v0, v15, v0, 1.0
	v_div_fmas_f32 v15, v19, v42, v58
	s_mov_b64 vcc, s[16:17]
	v_div_fixup_f32 v3, v15, v3, 1.0
	v_div_fmas_f32 v15, v21, v43, v59
	v_pk_mul_f32 v[0:1], v[24:25], v[0:1]
	v_div_fixup_f32 v2, v15, v2, 1.0
	v_and_b32_sdwa v15, v1, v110 dst_sel:DWORD dst_unused:UNUSED_PAD src0_sel:WORD_1 src1_sel:DWORD
	v_and_b32_sdwa v17, v0, v110 dst_sel:DWORD dst_unused:UNUSED_PAD src0_sel:WORD_1 src1_sel:DWORD
	v_pk_mul_f32 v[2:3], v[38:39], v[2:3]
	v_add3_u32 v0, v0, v17, s3
	v_add3_u32 v1, v1, v15, s3
	v_and_b32_sdwa v15, v3, v110 dst_sel:DWORD dst_unused:UNUSED_PAD src0_sel:WORD_1 src1_sel:DWORD
	v_and_b32_sdwa v17, v2, v110 dst_sel:DWORD dst_unused:UNUSED_PAD src0_sel:WORD_1 src1_sel:DWORD
	v_add3_u32 v3, v3, v15, s3
	v_add3_u32 v2, v2, v17, s3
	v_and_b32_e32 v3, 0xffff0000, v3
	v_and_b32_e32 v2, 0xffff0000, v2
	v_or_b32_sdwa v1, v3, v1 dst_sel:DWORD dst_unused:UNUSED_PAD src0_sel:DWORD src1_sel:WORD_1
	v_or_b32_sdwa v0, v2, v0 dst_sel:DWORD dst_unused:UNUSED_PAD src0_sel:DWORD src1_sel:WORD_1
	global_store_dwordx2 v[44:45], v[0:1], off
	s_nop 1
	v_mov_b32_e32 v0, v232
	v_mov_b32_e32 v1, v233
	v_mov_b32_e32 v2, v234
	v_mov_b32_e32 v3, v235
	s_nop 0
	s_waitcnt lgkmcnt(2)
	v_add_f32_e32 v15, v28, v0
	v_add_f32_e32 v2, v30, v2
	v_add_f32_e32 v3, v31, v3
	v_mul_f32_e32 v15, 0xbfb8aa3b, v15
	v_mul_f32_e32 v19, 0xbfb8aa3b, v2
	v_add_f32_e32 v17, v29, v1
	v_mul_f32_e32 v21, 0xbfb8aa3b, v3
	v_exp_f32_e32 v2, v15
	v_exp_f32_e32 v3, v19
	v_mul_f32_e32 v17, 0xbfb8aa3b, v17
	v_mov_b32_e32 v24, v244
	v_mov_b32_e32 v25, v245
	v_mov_b32_e32 v26, v246
	v_mov_b32_e32 v27, v247
	v_mov_b32_e32 v0, v24
	v_mov_b32_e32 v1, v26
	v_mov_b32_e32 v26, v25
	v_exp_f32_e32 v24, v17
	v_exp_f32_e32 v25, v21
	v_pk_add_f32 v[2:3], v[2:3], 1.0 op_sel_hi:[1,0]
	v_pk_add_f32 v[24:25], v[24:25], 1.0 op_sel_hi:[1,0]
	v_div_scale_f32 v15, s[10:11], v3, v3, 1.0
	v_div_scale_f32 v19, s[10:11], v2, v2, 1.0
	v_rcp_f32_e32 v36, v15
	v_div_scale_f32 v28, s[12:13], v25, v25, 1.0
	v_rcp_f32_e32 v37, v19
	v_div_scale_f32 v30, s[16:17], v24, v24, 1.0
	v_rcp_f32_e32 v38, v28
	v_rcp_f32_e32 v39, v30
	v_fma_f32 v40, -v15, v36, 1.0
	v_div_scale_f32 v17, vcc, 1.0, v3, 1.0
	v_fma_f32 v41, -v19, v37, 1.0
	v_fmac_f32_e32 v36, v40, v36
	v_div_scale_f32 v21, s[10:11], 1.0, v2, 1.0
	v_fma_f32 v42, -v28, v38, 1.0
	v_fmac_f32_e32 v37, v41, v37
	v_mul_f32_e32 v40, v17, v36
	v_div_scale_f32 v29, s[12:13], 1.0, v25, 1.0
	v_fma_f32 v43, -v30, v39, 1.0
	v_fmac_f32_e32 v38, v42, v38
	v_mul_f32_e32 v41, v21, v37
	v_fma_f32 v44, -v15, v40, v17
	v_div_scale_f32 v31, s[16:17], 1.0, v24, 1.0
	v_fmac_f32_e32 v39, v43, v39
	v_mul_f32_e32 v42, v29, v38
	v_fma_f32 v45, -v19, v41, v21
	v_fmac_f32_e32 v40, v44, v36
	v_mul_f32_e32 v43, v31, v39
	v_fma_f32 v46, -v28, v42, v29
	v_fmac_f32_e32 v41, v45, v37
	v_fma_f32 v15, -v15, v40, v17
	v_fma_f32 v47, -v30, v43, v31
	v_fmac_f32_e32 v42, v46, v38
	v_fma_f32 v17, -v19, v41, v21
	v_div_fmas_f32 v15, v15, v36, v40
	s_mov_b64 vcc, s[10:11]
	v_fmac_f32_e32 v43, v47, v39
	v_fma_f32 v19, -v28, v42, v29
	v_div_fixup_f32 v3, v15, v3, 1.0
	v_div_fmas_f32 v15, v17, v37, v41
	s_mov_b64 vcc, s[12:13]
	v_fma_f32 v21, -v30, v43, v31
	v_div_fixup_f32 v2, v15, v2, 1.0
	v_div_fmas_f32 v15, v19, v38, v42
	s_mov_b64 vcc, s[16:17]
	v_pk_mul_f32 v[0:1], v[0:1], v[2:3]
	v_div_fmas_f32 v2, v21, v39, v43
	v_div_fixup_f32 v3, v15, v25, 1.0
	v_div_fixup_f32 v2, v2, v24, 1.0
	v_and_b32_sdwa v15, v1, v110 dst_sel:DWORD dst_unused:UNUSED_PAD src0_sel:WORD_1 src1_sel:DWORD
	v_and_b32_sdwa v17, v0, v110 dst_sel:DWORD dst_unused:UNUSED_PAD src0_sel:WORD_1 src1_sel:DWORD
	v_pk_mul_f32 v[2:3], v[26:27], v[2:3]
	v_add3_u32 v0, v0, v17, s3
	v_add3_u32 v1, v1, v15, s3
	v_and_b32_sdwa v15, v3, v110 dst_sel:DWORD dst_unused:UNUSED_PAD src0_sel:WORD_1 src1_sel:DWORD
	v_and_b32_sdwa v17, v2, v110 dst_sel:DWORD dst_unused:UNUSED_PAD src0_sel:WORD_1 src1_sel:DWORD
	v_add3_u32 v3, v3, v15, s3
	v_add3_u32 v2, v2, v17, s3
	v_and_b32_e32 v3, 0xffff0000, v3
	v_and_b32_e32 v2, 0xffff0000, v2
	v_or_b32_sdwa v1, v3, v1 dst_sel:DWORD dst_unused:UNUSED_PAD src0_sel:DWORD src1_sel:WORD_1
	v_or_b32_sdwa v0, v2, v0 dst_sel:DWORD dst_unused:UNUSED_PAD src0_sel:DWORD src1_sel:WORD_1
	global_store_dwordx2 v[48:49], v[0:1], off
	s_nop 1
	v_mov_b32_e32 v0, v232
	v_mov_b32_e32 v1, v233
	v_mov_b32_e32 v2, v234
	v_mov_b32_e32 v3, v235
	s_nop 0
	s_waitcnt lgkmcnt(1)
	v_add_f32_e32 v15, v32, v0
	v_add_f32_e32 v2, v34, v2
	v_add_f32_e32 v3, v35, v3
	v_mul_f32_e32 v15, 0xbfb8aa3b, v15
	v_mul_f32_e32 v19, 0xbfb8aa3b, v2
	v_add_f32_e32 v17, v33, v1
	v_mul_f32_e32 v21, 0xbfb8aa3b, v3
	v_exp_f32_e32 v2, v15
	v_exp_f32_e32 v3, v19
	v_mul_f32_e32 v17, 0xbfb8aa3b, v17
	v_mov_b32_e32 v24, v248
	v_mov_b32_e32 v25, v249
	v_mov_b32_e32 v26, v250
	v_mov_b32_e32 v27, v251
	v_mov_b32_e32 v0, v24
	v_mov_b32_e32 v1, v26
	v_mov_b32_e32 v26, v25
	v_exp_f32_e32 v24, v17
	v_exp_f32_e32 v25, v21
	v_pk_add_f32 v[2:3], v[2:3], 1.0 op_sel_hi:[1,0]
	v_pk_add_f32 v[24:25], v[24:25], 1.0 op_sel_hi:[1,0]
	v_div_scale_f32 v15, s[10:11], v3, v3, 1.0
	v_div_scale_f32 v19, s[10:11], v2, v2, 1.0
	v_rcp_f32_e32 v32, v15
	v_div_scale_f32 v28, s[12:13], v25, v25, 1.0
	v_rcp_f32_e32 v33, v19
	v_div_scale_f32 v30, s[16:17], v24, v24, 1.0
	v_rcp_f32_e32 v34, v28
	v_rcp_f32_e32 v35, v30
	v_fma_f32 v36, -v15, v32, 1.0
	v_div_scale_f32 v17, vcc, 1.0, v3, 1.0
	v_fma_f32 v37, -v19, v33, 1.0
	v_fmac_f32_e32 v32, v36, v32
	v_div_scale_f32 v21, s[10:11], 1.0, v2, 1.0
	v_fma_f32 v38, -v28, v34, 1.0
	v_fmac_f32_e32 v33, v37, v33
	v_mul_f32_e32 v36, v17, v32
	v_div_scale_f32 v29, s[12:13], 1.0, v25, 1.0
	v_fma_f32 v39, -v30, v35, 1.0
	v_fmac_f32_e32 v34, v38, v34
	v_mul_f32_e32 v37, v21, v33
	v_fma_f32 v40, -v15, v36, v17
	v_div_scale_f32 v31, s[16:17], 1.0, v24, 1.0
	v_fmac_f32_e32 v35, v39, v35
	v_mul_f32_e32 v38, v29, v34
	v_fma_f32 v41, -v19, v37, v21
	v_fmac_f32_e32 v36, v40, v32
	v_mul_f32_e32 v39, v31, v35
	v_fma_f32 v42, -v28, v38, v29
	v_fmac_f32_e32 v37, v41, v33
	v_fma_f32 v15, -v15, v36, v17
	v_fma_f32 v43, -v30, v39, v31
	v_fmac_f32_e32 v38, v42, v34
	v_fma_f32 v17, -v19, v37, v21
	v_div_fmas_f32 v15, v15, v32, v36
	s_mov_b64 vcc, s[10:11]
	v_fmac_f32_e32 v39, v43, v35
	v_fma_f32 v19, -v28, v38, v29
	v_div_fixup_f32 v3, v15, v3, 1.0
	v_div_fmas_f32 v15, v17, v33, v37
	s_mov_b64 vcc, s[12:13]
	v_fma_f32 v21, -v30, v39, v31
	v_div_fixup_f32 v2, v15, v2, 1.0
	v_div_fmas_f32 v15, v19, v34, v38
	s_mov_b64 vcc, s[16:17]
	v_pk_mul_f32 v[0:1], v[0:1], v[2:3]
	v_div_fmas_f32 v2, v21, v35, v39
	v_div_fixup_f32 v3, v15, v25, 1.0
	v_div_fixup_f32 v2, v2, v24, 1.0
	v_and_b32_sdwa v15, v1, v110 dst_sel:DWORD dst_unused:UNUSED_PAD src0_sel:WORD_1 src1_sel:DWORD
	v_and_b32_sdwa v17, v0, v110 dst_sel:DWORD dst_unused:UNUSED_PAD src0_sel:WORD_1 src1_sel:DWORD
	v_pk_mul_f32 v[2:3], v[26:27], v[2:3]
	v_add3_u32 v0, v0, v17, s3
	v_add3_u32 v1, v1, v15, s3
	v_and_b32_sdwa v15, v3, v110 dst_sel:DWORD dst_unused:UNUSED_PAD src0_sel:WORD_1 src1_sel:DWORD
	v_and_b32_sdwa v17, v2, v110 dst_sel:DWORD dst_unused:UNUSED_PAD src0_sel:WORD_1 src1_sel:DWORD
	v_add3_u32 v3, v3, v15, s3
	v_add3_u32 v2, v2, v17, s3
	v_and_b32_e32 v3, 0xffff0000, v3
	v_and_b32_e32 v2, 0xffff0000, v2
	v_or_b32_sdwa v1, v3, v1 dst_sel:DWORD dst_unused:UNUSED_PAD src0_sel:DWORD src1_sel:WORD_1
	v_or_b32_sdwa v0, v2, v0 dst_sel:DWORD dst_unused:UNUSED_PAD src0_sel:DWORD src1_sel:WORD_1
	global_store_dwordx2 v[52:53], v[0:1], off
	s_nop 1
	v_mov_b32_e32 v0, v232
	v_mov_b32_e32 v1, v233
	v_mov_b32_e32 v2, v234
	v_mov_b32_e32 v3, v235
	s_nop 0
	s_waitcnt lgkmcnt(0)
	v_add_f32_e32 v4, v4, v0
	v_add_f32_e32 v2, v6, v2
	v_add_f32_e32 v3, v7, v3
	v_mul_f32_e32 v4, 0xbfb8aa3b, v4
	v_mul_f32_e32 v6, 0xbfb8aa3b, v2
	v_add_f32_e32 v5, v5, v1
	v_mul_f32_e32 v7, 0xbfb8aa3b, v3
	v_exp_f32_e32 v2, v4
	v_exp_f32_e32 v3, v6
	v_mul_f32_e32 v5, 0xbfb8aa3b, v5
	v_exp_f32_e32 v4, v5
	v_exp_f32_e32 v5, v7
	v_pk_add_f32 v[2:3], v[2:3], 1.0 op_sel_hi:[1,0]
	v_mov_b32_e32 v24, v252
	v_mov_b32_e32 v25, v253
	v_mov_b32_e32 v26, v254
	v_mov_b32_e32 v27, v255
	v_mov_b32_e32 v0, v24
	v_div_scale_f32 v6, s[10:11], v3, v3, 1.0
	v_pk_add_f32 v[4:5], v[4:5], 1.0 op_sel_hi:[1,0]
	v_div_scale_f32 v15, s[10:11], v2, v2, 1.0
	v_rcp_f32_e32 v28, v6
	v_div_scale_f32 v19, s[12:13], v5, v5, 1.0
	v_rcp_f32_e32 v29, v15
	v_div_scale_f32 v24, s[16:17], v4, v4, 1.0
	v_rcp_f32_e32 v30, v19
	v_rcp_f32_e32 v31, v24
	v_fma_f32 v32, -v6, v28, 1.0
	v_div_scale_f32 v7, vcc, 1.0, v3, 1.0
	v_fma_f32 v33, -v15, v29, 1.0
	v_fmac_f32_e32 v28, v32, v28
	v_div_scale_f32 v17, s[10:11], 1.0, v2, 1.0
	v_fma_f32 v34, -v19, v30, 1.0
	v_fmac_f32_e32 v29, v33, v29
	v_mul_f32_e32 v32, v7, v28
	v_div_scale_f32 v21, s[12:13], 1.0, v5, 1.0
	v_fma_f32 v35, -v24, v31, 1.0
	v_fmac_f32_e32 v30, v34, v30
	v_mul_f32_e32 v33, v17, v29
	v_fma_f32 v36, -v6, v32, v7
	v_mov_b32_e32 v1, v26
	v_mov_b32_e32 v26, v25
	v_div_scale_f32 v25, s[16:17], 1.0, v4, 1.0
	v_fmac_f32_e32 v31, v35, v31
	v_mul_f32_e32 v34, v21, v30
	v_fma_f32 v37, -v15, v33, v17
	v_fmac_f32_e32 v32, v36, v28
	v_mul_f32_e32 v35, v25, v31
	v_fma_f32 v38, -v19, v34, v21
	v_fmac_f32_e32 v33, v37, v29
	v_fma_f32 v6, -v6, v32, v7
	v_fma_f32 v39, -v24, v35, v25
	v_fmac_f32_e32 v34, v38, v30
	v_fma_f32 v7, -v15, v33, v17
	v_div_fmas_f32 v6, v6, v28, v32
	s_mov_b64 vcc, s[10:11]
	v_fmac_f32_e32 v35, v39, v31
	v_fma_f32 v15, -v19, v34, v21
	v_div_fixup_f32 v3, v6, v3, 1.0
	v_div_fmas_f32 v6, v7, v29, v33
	s_mov_b64 vcc, s[12:13]
	v_fma_f32 v17, -v24, v35, v25
	v_div_fixup_f32 v2, v6, v2, 1.0
	v_div_fmas_f32 v6, v15, v30, v34
	s_mov_b64 vcc, s[16:17]
	v_pk_mul_f32 v[0:1], v[0:1], v[2:3]
	v_div_fmas_f32 v2, v17, v31, v35
	v_div_fixup_f32 v3, v6, v5, 1.0
	v_div_fixup_f32 v2, v2, v4, 1.0
	v_and_b32_sdwa v4, v1, v110 dst_sel:DWORD dst_unused:UNUSED_PAD src0_sel:WORD_1 src1_sel:DWORD
	v_and_b32_sdwa v5, v0, v110 dst_sel:DWORD dst_unused:UNUSED_PAD src0_sel:WORD_1 src1_sel:DWORD
	v_pk_mul_f32 v[2:3], v[26:27], v[2:3]
	v_add3_u32 v0, v0, v5, s3
	v_add3_u32 v1, v1, v4, s3
	v_and_b32_sdwa v4, v3, v110 dst_sel:DWORD dst_unused:UNUSED_PAD src0_sel:WORD_1 src1_sel:DWORD
	v_and_b32_sdwa v5, v2, v110 dst_sel:DWORD dst_unused:UNUSED_PAD src0_sel:WORD_1 src1_sel:DWORD
	v_add3_u32 v3, v3, v4, s3
	v_add3_u32 v2, v2, v5, s3
	v_and_b32_e32 v3, 0xffff0000, v3
	v_and_b32_e32 v2, 0xffff0000, v2
	v_or_b32_sdwa v1, v3, v1 dst_sel:DWORD dst_unused:UNUSED_PAD src0_sel:DWORD src1_sel:WORD_1
	v_or_b32_sdwa v0, v2, v0 dst_sel:DWORD dst_unused:UNUSED_PAD src0_sel:DWORD src1_sel:WORD_1
	global_store_dwordx2 v[22:23], v[0:1], off
	s_cbranch_scc1 .LBB0_667
	s_barrier
	s_branch .LBB0_646

.LBB0_763:
	v_lshl_add_u64 v[4:5], v[40:41], 0, v[64:65]
	v_add_co_u32_e32 v4, vcc, s49, v4
	v_lshl_add_u64 v[0:1], v[48:49], 0, v[64:65]
	s_nop 0
	v_addc_co_u32_e32 v5, vcc, 0, v5, vcc
	global_load_dwordx4 v[56:59], v[0:1], off
	s_nop 0
	global_load_dwordx4 v[158:161], v[4:5], off
	v_lshl_add_u64 v[190:191], v[32:33], 0, v[64:65]
	v_lshl_add_u64 v[4:5], v[52:53], 0, v[64:65]
	v_add_co_u32_e32 v4, vcc, s49, v4
	v_lshl_add_u64 v[0:1], v[50:51], 0, v[64:65]
	s_nop 0
	v_addc_co_u32_e32 v5, vcc, 0, v5, vcc
	global_load_dwordx4 v[60:63], v[0:1], off offset:-8
	s_nop 0
	global_load_dwordx4 v[162:165], v[4:5], off
	v_lshl_add_u64 v[192:193], v[54:55], 0, v[64:65]
	v_lshl_add_u64 v[4:5], v[44:45], 0, v[64:65]
	v_add_co_u32_e32 v4, vcc, s49, v4
	v_lshl_add_u64 v[0:1], v[42:43], 0, v[64:65]
	s_nop 0
	v_addc_co_u32_e32 v5, vcc, 0, v5, vcc
	global_load_dwordx4 v[126:129], v[0:1], off offset:-8
	s_nop 0
	global_load_dwordx4 v[166:169], v[4:5], off
	v_lshl_add_u64 v[194:195], v[46:47], 0, v[64:65]
	v_lshl_add_u64 v[4:5], v[36:37], 0, v[64:65]
	v_add_co_u32_e32 v4, vcc, s49, v4
	v_lshl_add_u64 v[0:1], v[34:35], 0, v[64:65]
	s_nop 0
	v_addc_co_u32_e32 v5, vcc, 0, v5, vcc
	global_load_dwordx4 v[130:133], v[0:1], off offset:-8
	s_nop 0
	global_load_dwordx4 v[170:173], v[4:5], off
	v_lshl_add_u64 v[220:221], v[38:39], 0, v[64:65]
	v_lshl_add_u64 v[48:49], v[48:49], 0, s[20:21]
	v_lshl_add_u64 v[32:33], v[32:33], 0, s[20:21]
	v_lshl_add_u64 v[40:41], v[40:41], 0, s[22:23]
	v_lshl_add_u64 v[50:51], v[50:51], 0, s[20:21]
	v_lshl_add_u64 v[54:55], v[54:55], 0, s[20:21]
	v_lshl_add_u64 v[52:53], v[52:53], 0, s[22:23]
	v_lshl_add_u64 v[42:43], v[42:43], 0, s[20:21]
	v_lshl_add_u64 v[46:47], v[46:47], 0, s[20:21]
	v_lshl_add_u64 v[44:45], v[44:45], 0, s[22:23]
	v_lshl_add_u64 v[34:35], v[34:35], 0, s[20:21]
	v_lshl_add_u64 v[38:39], v[38:39], 0, s[20:21]
	v_lshl_add_u64 v[36:37], v[36:37], 0, s[22:23]
	v_lshl_add_u64 v[4:5], v[40:41], 0, v[64:65]
	v_add_co_u32_e32 v4, vcc, s49, v4
	v_lshl_add_u64 v[0:1], v[48:49], 0, v[64:65]
	s_nop 0
	v_addc_co_u32_e32 v5, vcc, 0, v5, vcc
	global_load_dwordx4 v[134:137], v[0:1], off
	s_nop 0
	global_load_dwordx4 v[174:177], v[4:5], off
	v_lshl_add_u64 v[222:223], v[32:33], 0, v[64:65]
	v_lshl_add_u64 v[4:5], v[52:53], 0, v[64:65]
	v_add_co_u32_e32 v4, vcc, s49, v4
	v_lshl_add_u64 v[0:1], v[50:51], 0, v[64:65]
	s_nop 0
	v_addc_co_u32_e32 v5, vcc, 0, v5, vcc
	global_load_dwordx4 v[138:141], v[0:1], off offset:-8
	s_nop 0
	global_load_dwordx4 v[178:181], v[4:5], off
	v_lshl_add_u64 v[224:225], v[54:55], 0, v[64:65]
	v_lshl_add_u64 v[4:5], v[44:45], 0, v[64:65]
	v_add_co_u32_e32 v4, vcc, s49, v4
	v_lshl_add_u64 v[0:1], v[42:43], 0, v[64:65]
	s_nop 0
	v_addc_co_u32_e32 v5, vcc, 0, v5, vcc
	global_load_dwordx4 v[142:145], v[0:1], off offset:-8
	s_nop 0
	global_load_dwordx4 v[182:185], v[4:5], off
	v_lshl_add_u64 v[226:227], v[46:47], 0, v[64:65]
	v_lshl_add_u64 v[4:5], v[36:37], 0, v[64:65]
	v_add_co_u32_e32 v4, vcc, s49, v4
	v_lshl_add_u64 v[0:1], v[34:35], 0, v[64:65]
	s_nop 0
	v_addc_co_u32_e32 v5, vcc, 0, v5, vcc
	global_load_dwordx4 v[154:157], v[0:1], off offset:-8
	s_nop 0
	global_load_dwordx4 v[186:189], v[4:5], off
	v_lshl_add_u64 v[228:229], v[38:39], 0, v[64:65]
	ds_read_b128 v[8:11], v84
	ds_read_b128 v[20:23], v90
	s_waitcnt vmcnt(14) lgkmcnt(1)
	v_pk_fma_f32 v[56:57], v[8:9], v[158:159], v[56:57]
	v_pk_fma_f32 v[58:59], v[10:11], v[160:161], v[58:59]
	global_store_dwordx4 v[190:191], v[56:59], off
	ds_read_b128 v[8:11], v87
	s_waitcnt vmcnt(13) lgkmcnt(1)
	v_pk_fma_f32 v[60:61], v[20:21], v[162:163], v[60:61]
	v_pk_fma_f32 v[62:63], v[22:23], v[164:165], v[62:63]
	global_store_dwordx4 v[192:193], v[60:63], off offset:-8
	ds_read_b128 v[20:23], v83
	s_waitcnt vmcnt(12) lgkmcnt(1)
	v_pk_fma_f32 v[126:127], v[8:9], v[166:167], v[126:127]
	v_pk_fma_f32 v[128:129], v[10:11], v[168:169], v[128:129]
	global_store_dwordx4 v[194:195], v[126:129], off offset:-8
	ds_read_b128 v[8:11], v84 offset:16896
	s_waitcnt vmcnt(11) lgkmcnt(1)
	v_pk_fma_f32 v[130:131], v[20:21], v[170:171], v[130:131]
	v_pk_fma_f32 v[132:133], v[22:23], v[172:173], v[132:133]
	global_store_dwordx4 v[220:221], v[130:133], off offset:-8
	ds_read_b128 v[20:23], v90 offset:16896
	s_waitcnt vmcnt(10) lgkmcnt(1)
	v_pk_fma_f32 v[134:135], v[8:9], v[174:175], v[134:135]
	v_pk_fma_f32 v[136:137], v[10:11], v[176:177], v[136:137]
	global_store_dwordx4 v[222:223], v[134:137], off
	ds_read_b128 v[8:11], v87 offset:16896
	s_waitcnt vmcnt(9) lgkmcnt(1)
	v_pk_fma_f32 v[138:139], v[20:21], v[178:179], v[138:139]
	v_pk_fma_f32 v[140:141], v[22:23], v[180:181], v[140:141]
	global_store_dwordx4 v[224:225], v[138:141], off offset:-8
	ds_read_b128 v[20:23], v83 offset:16896
	s_waitcnt vmcnt(8) lgkmcnt(1)
	v_pk_fma_f32 v[142:143], v[8:9], v[182:183], v[142:143]
	v_pk_fma_f32 v[144:145], v[10:11], v[184:185], v[144:145]
	global_store_dwordx4 v[226:227], v[142:145], off offset:-8
	s_waitcnt vmcnt(7) lgkmcnt(0)
	v_pk_fma_f32 v[154:155], v[20:21], v[186:187], v[154:155]
	v_pk_fma_f32 v[156:157], v[22:23], v[188:189], v[156:157]
	global_store_dwordx4 v[228:229], v[154:157], off offset:-8
	s_mov_b32 s14, 0x8400
	s_mov_b64 s[24:25], 0
	s_barrier
